# v51 + skip-path-only accumulator zeroing (127 v_mov per tile) moved off the K-loop path in 8 GEMM tile loops
# speedup vs baseline: 1.0105x; 1.0105x over previous
.LBB0_140:
	s_and_b64 vcc, exec, s[0:1]
	s_cbranch_vccz .Lzskip_1
	v_mov_b32_e32 v123, 0
	v_mov_b32_e32 v122, v123
	v_mov_b32_e32 v121, v123
	v_mov_b32_e32 v120, v123
	v_mov_b32_e32 v119, v123
	v_mov_b32_e32 v118, v123
	v_mov_b32_e32 v117, v123
	v_mov_b32_e32 v116, v123
	v_mov_b32_e32 v111, v123
	v_mov_b32_e32 v110, v123
	v_mov_b32_e32 v109, v123
	v_mov_b32_e32 v108, v123
	v_mov_b32_e32 v103, v123
	v_mov_b32_e32 v102, v123
	v_mov_b32_e32 v101, v123
	v_mov_b32_e32 v100, v123
	v_mov_b32_e32 v95, v123
	v_mov_b32_e32 v94, v123
	v_mov_b32_e32 v93, v123
	v_mov_b32_e32 v92, v123
	v_mov_b32_e32 v87, v123
	v_mov_b32_e32 v86, v123
	v_mov_b32_e32 v85, v123
	v_mov_b32_e32 v84, v123
	v_mov_b32_e32 v79, v123
	v_mov_b32_e32 v78, v123
	v_mov_b32_e32 v77, v123
	v_mov_b32_e32 v76, v123
	v_mov_b32_e32 v71, v123
	v_mov_b32_e32 v70, v123
	v_mov_b32_e32 v69, v123
	v_mov_b32_e32 v68, v123
	v_mov_b32_e32 v127, v123
	v_mov_b32_e32 v126, v123
	v_mov_b32_e32 v125, v123
	v_mov_b32_e32 v124, v123
	v_mov_b32_e32 v115, v123
	v_mov_b32_e32 v114, v123
	v_mov_b32_e32 v113, v123
	v_mov_b32_e32 v112, v123
	v_mov_b32_e32 v107, v123
	v_mov_b32_e32 v106, v123
	v_mov_b32_e32 v105, v123
	v_mov_b32_e32 v104, v123
	v_mov_b32_e32 v99, v123
	v_mov_b32_e32 v98, v123
	v_mov_b32_e32 v97, v123
	v_mov_b32_e32 v96, v123
	v_mov_b32_e32 v91, v123
	v_mov_b32_e32 v90, v123
	v_mov_b32_e32 v89, v123
	v_mov_b32_e32 v88, v123
	v_mov_b32_e32 v83, v123
	v_mov_b32_e32 v82, v123
	v_mov_b32_e32 v81, v123
	v_mov_b32_e32 v80, v123
	v_mov_b32_e32 v75, v123
	v_mov_b32_e32 v74, v123
	v_mov_b32_e32 v73, v123
	v_mov_b32_e32 v72, v123
	v_mov_b32_e32 v67, v123
	v_mov_b32_e32 v66, v123
	v_mov_b32_e32 v65, v123
	v_mov_b32_e32 v64, v123
	v_mov_b32_e32 v63, v123
	v_mov_b32_e32 v62, v123
	v_mov_b32_e32 v61, v123
	v_mov_b32_e32 v60, v123
	v_mov_b32_e32 v55, v123
	v_mov_b32_e32 v54, v123
	v_mov_b32_e32 v53, v123
	v_mov_b32_e32 v52, v123
	v_mov_b32_e32 v47, v123
	v_mov_b32_e32 v46, v123
	v_mov_b32_e32 v45, v123
	v_mov_b32_e32 v44, v123
	v_mov_b32_e32 v39, v123
	v_mov_b32_e32 v38, v123
	v_mov_b32_e32 v37, v123
	v_mov_b32_e32 v36, v123
	v_mov_b32_e32 v31, v123
	v_mov_b32_e32 v30, v123
	v_mov_b32_e32 v29, v123
	v_mov_b32_e32 v28, v123
	v_mov_b32_e32 v23, v123
	v_mov_b32_e32 v22, v123
	v_mov_b32_e32 v21, v123
	v_mov_b32_e32 v20, v123
	v_mov_b32_e32 v15, v123
	v_mov_b32_e32 v14, v123
	v_mov_b32_e32 v13, v123
	v_mov_b32_e32 v12, v123
	v_mov_b32_e32 v7, v123
	v_mov_b32_e32 v6, v123
	v_mov_b32_e32 v5, v123
	v_mov_b32_e32 v4, v123
	v_mov_b32_e32 v59, v123
	v_mov_b32_e32 v58, v123
	v_mov_b32_e32 v57, v123
	v_mov_b32_e32 v56, v123
	v_mov_b32_e32 v51, v123
	v_mov_b32_e32 v50, v123
	v_mov_b32_e32 v49, v123
	v_mov_b32_e32 v48, v123
	v_mov_b32_e32 v43, v123
	v_mov_b32_e32 v42, v123
	v_mov_b32_e32 v41, v123
	v_mov_b32_e32 v40, v123
	v_mov_b32_e32 v35, v123
	v_mov_b32_e32 v34, v123
	v_mov_b32_e32 v33, v123
	v_mov_b32_e32 v32, v123
	v_mov_b32_e32 v27, v123
	v_mov_b32_e32 v26, v123
	v_mov_b32_e32 v25, v123
	v_mov_b32_e32 v24, v123
	v_mov_b32_e32 v19, v123
	v_mov_b32_e32 v18, v123
	v_mov_b32_e32 v17, v123
	v_mov_b32_e32 v16, v123
	v_mov_b32_e32 v11, v123
	v_mov_b32_e32 v10, v123
	v_mov_b32_e32 v9, v123
	v_mov_b32_e32 v8, v123
	v_mov_b32_e32 v3, v123
	v_mov_b32_e32 v2, v123
	v_mov_b32_e32 v1, v123
	v_mov_b32_e32 v0, v123
	s_branch .LBB0_143
.Lzskip_1:
	s_add_u32 s20, s20, 0x80
	s_addc_u32 s21, s21, 0
	s_add_u32 s52, s22, 0x100
	v_mov_b32_e32 v0, 0
	s_addc_u32 s53, s23, 0
	s_mov_b32 s22, 0
	v_mov_b32_e32 v1, v0
	v_mov_b32_e32 v2, v0
	v_mov_b32_e32 v3, v0
	v_mov_b32_e32 v8, v0
	v_mov_b32_e32 v9, v0
	v_mov_b32_e32 v10, v0
	v_mov_b32_e32 v11, v0
	v_mov_b32_e32 v16, v0
	v_mov_b32_e32 v17, v0
	v_mov_b32_e32 v18, v0
	v_mov_b32_e32 v19, v0
	v_mov_b32_e32 v24, v0
	v_mov_b32_e32 v25, v0
	v_mov_b32_e32 v26, v0
	v_mov_b32_e32 v27, v0
	v_mov_b32_e32 v32, v0
	v_mov_b32_e32 v33, v0
	v_mov_b32_e32 v34, v0
	v_mov_b32_e32 v35, v0
	v_mov_b32_e32 v40, v0
	v_mov_b32_e32 v41, v0
	v_mov_b32_e32 v42, v0
	v_mov_b32_e32 v43, v0
	v_mov_b32_e32 v48, v0
	v_mov_b32_e32 v49, v0
	v_mov_b32_e32 v50, v0
	v_mov_b32_e32 v51, v0
	v_mov_b32_e32 v56, v0
	v_mov_b32_e32 v57, v0
	v_mov_b32_e32 v58, v0
	v_mov_b32_e32 v59, v0
	v_mov_b32_e32 v4, v0
	v_mov_b32_e32 v5, v0
	v_mov_b32_e32 v6, v0
	v_mov_b32_e32 v7, v0
	v_mov_b32_e32 v12, v0
	v_mov_b32_e32 v13, v0
	v_mov_b32_e32 v14, v0
	v_mov_b32_e32 v15, v0
	v_mov_b32_e32 v20, v0
	v_mov_b32_e32 v21, v0
	v_mov_b32_e32 v22, v0
	v_mov_b32_e32 v23, v0
	v_mov_b32_e32 v28, v0
	v_mov_b32_e32 v29, v0
	v_mov_b32_e32 v30, v0
	v_mov_b32_e32 v31, v0
	v_mov_b32_e32 v36, v0
	v_mov_b32_e32 v37, v0
	v_mov_b32_e32 v38, v0
	v_mov_b32_e32 v39, v0
	v_mov_b32_e32 v44, v0
	v_mov_b32_e32 v45, v0
	v_mov_b32_e32 v46, v0
	v_mov_b32_e32 v47, v0
	v_mov_b32_e32 v52, v0
	v_mov_b32_e32 v53, v0
	v_mov_b32_e32 v54, v0
	v_mov_b32_e32 v55, v0
	v_mov_b32_e32 v60, v0
	v_mov_b32_e32 v61, v0
	v_mov_b32_e32 v62, v0
	v_mov_b32_e32 v63, v0
	v_mov_b32_e32 v64, v0
	v_mov_b32_e32 v65, v0
	v_mov_b32_e32 v66, v0
	v_mov_b32_e32 v67, v0
	v_mov_b32_e32 v72, v0
	v_mov_b32_e32 v73, v0
	v_mov_b32_e32 v74, v0
	v_mov_b32_e32 v75, v0
	v_mov_b32_e32 v80, v0
	v_mov_b32_e32 v81, v0
	v_mov_b32_e32 v82, v0
	v_mov_b32_e32 v83, v0
	v_mov_b32_e32 v88, v0
	v_mov_b32_e32 v89, v0
	v_mov_b32_e32 v90, v0
	v_mov_b32_e32 v91, v0
	v_mov_b32_e32 v96, v0
	v_mov_b32_e32 v97, v0
	v_mov_b32_e32 v98, v0
	v_mov_b32_e32 v99, v0
	v_mov_b32_e32 v104, v0
	v_mov_b32_e32 v105, v0
	v_mov_b32_e32 v106, v0
	v_mov_b32_e32 v107, v0
	v_mov_b32_e32 v112, v0
	v_mov_b32_e32 v113, v0
	v_mov_b32_e32 v114, v0
	v_mov_b32_e32 v115, v0
	v_mov_b32_e32 v124, v0
	v_mov_b32_e32 v125, v0
	v_mov_b32_e32 v126, v0
	v_mov_b32_e32 v127, v0
	v_mov_b32_e32 v68, v0
	v_mov_b32_e32 v69, v0
	v_mov_b32_e32 v70, v0
	v_mov_b32_e32 v71, v0
	v_mov_b32_e32 v76, v0
	v_mov_b32_e32 v77, v0
	v_mov_b32_e32 v78, v0
	v_mov_b32_e32 v79, v0
	v_mov_b32_e32 v84, v0
	v_mov_b32_e32 v85, v0
	v_mov_b32_e32 v86, v0
	v_mov_b32_e32 v87, v0
	v_mov_b32_e32 v92, v0
	v_mov_b32_e32 v93, v0
	v_mov_b32_e32 v94, v0
	v_mov_b32_e32 v95, v0
	v_mov_b32_e32 v100, v0
	v_mov_b32_e32 v101, v0
	v_mov_b32_e32 v102, v0
	v_mov_b32_e32 v103, v0
	v_mov_b32_e32 v108, v0
	v_mov_b32_e32 v109, v0
	v_mov_b32_e32 v110, v0
	v_mov_b32_e32 v111, v0
	v_mov_b32_e32 v116, v0
	v_mov_b32_e32 v117, v0
	v_mov_b32_e32 v118, v0
	v_mov_b32_e32 v119, v0
	v_mov_b32_e32 v120, v0
	v_mov_b32_e32 v121, v0
	v_mov_b32_e32 v122, v0
	v_mov_b32_e32 v123, v0

.LBB0_321:
	s_andn2_b64 vcc, exec, s[38:39]
	s_cbranch_vccz .Lzskip_2
	v_mov_b32_e32 v127, 0
	v_mov_b32_e32 v126, v127
	v_mov_b32_e32 v125, v127
	v_mov_b32_e32 v124, v127
	v_mov_b32_e32 v123, v127
	v_mov_b32_e32 v122, v127
	v_mov_b32_e32 v121, v127
	v_mov_b32_e32 v120, v127
	v_mov_b32_e32 v111, v127
	v_mov_b32_e32 v110, v127
	v_mov_b32_e32 v109, v127
	v_mov_b32_e32 v108, v127
	v_mov_b32_e32 v107, v127
	v_mov_b32_e32 v106, v127
	v_mov_b32_e32 v105, v127
	v_mov_b32_e32 v104, v127
	v_mov_b32_e32 v95, v127
	v_mov_b32_e32 v94, v127
	v_mov_b32_e32 v93, v127
	v_mov_b32_e32 v92, v127
	v_mov_b32_e32 v91, v127
	v_mov_b32_e32 v90, v127
	v_mov_b32_e32 v89, v127
	v_mov_b32_e32 v88, v127
	v_mov_b32_e32 v79, v127
	v_mov_b32_e32 v78, v127
	v_mov_b32_e32 v77, v127
	v_mov_b32_e32 v76, v127
	v_mov_b32_e32 v75, v127
	v_mov_b32_e32 v74, v127
	v_mov_b32_e32 v73, v127
	v_mov_b32_e32 v72, v127
	v_mov_b32_e32 v119, v127
	v_mov_b32_e32 v118, v127
	v_mov_b32_e32 v117, v127
	v_mov_b32_e32 v116, v127
	v_mov_b32_e32 v115, v127
	v_mov_b32_e32 v114, v127
	v_mov_b32_e32 v113, v127
	v_mov_b32_e32 v112, v127
	v_mov_b32_e32 v103, v127
	v_mov_b32_e32 v102, v127
	v_mov_b32_e32 v101, v127
	v_mov_b32_e32 v100, v127
	v_mov_b32_e32 v99, v127
	v_mov_b32_e32 v98, v127
	v_mov_b32_e32 v97, v127
	v_mov_b32_e32 v96, v127
	v_mov_b32_e32 v87, v127
	v_mov_b32_e32 v86, v127
	v_mov_b32_e32 v85, v127
	v_mov_b32_e32 v84, v127
	v_mov_b32_e32 v83, v127
	v_mov_b32_e32 v82, v127
	v_mov_b32_e32 v81, v127
	v_mov_b32_e32 v80, v127
	v_mov_b32_e32 v71, v127
	v_mov_b32_e32 v70, v127
	v_mov_b32_e32 v69, v127
	v_mov_b32_e32 v68, v127
	v_mov_b32_e32 v67, v127
	v_mov_b32_e32 v66, v127
	v_mov_b32_e32 v65, v127
	v_mov_b32_e32 v64, v127
	v_mov_b32_e32 v63, v127
	v_mov_b32_e32 v62, v127
	v_mov_b32_e32 v61, v127
	v_mov_b32_e32 v60, v127
	v_mov_b32_e32 v59, v127
	v_mov_b32_e32 v58, v127
	v_mov_b32_e32 v57, v127
	v_mov_b32_e32 v56, v127
	v_mov_b32_e32 v47, v127
	v_mov_b32_e32 v46, v127
	v_mov_b32_e32 v45, v127
	v_mov_b32_e32 v44, v127
	v_mov_b32_e32 v43, v127
	v_mov_b32_e32 v42, v127
	v_mov_b32_e32 v41, v127
	v_mov_b32_e32 v40, v127
	v_mov_b32_e32 v31, v127
	v_mov_b32_e32 v30, v127
	v_mov_b32_e32 v29, v127
	v_mov_b32_e32 v28, v127
	v_mov_b32_e32 v27, v127
	v_mov_b32_e32 v26, v127
	v_mov_b32_e32 v25, v127
	v_mov_b32_e32 v24, v127
	v_mov_b32_e32 v15, v127
	v_mov_b32_e32 v14, v127
	v_mov_b32_e32 v13, v127
	v_mov_b32_e32 v12, v127
	v_mov_b32_e32 v11, v127
	v_mov_b32_e32 v10, v127
	v_mov_b32_e32 v9, v127
	v_mov_b32_e32 v8, v127
	v_mov_b32_e32 v55, v127
	v_mov_b32_e32 v54, v127
	v_mov_b32_e32 v53, v127
	v_mov_b32_e32 v52, v127
	v_mov_b32_e32 v51, v127
	v_mov_b32_e32 v50, v127
	v_mov_b32_e32 v49, v127
	v_mov_b32_e32 v48, v127
	v_mov_b32_e32 v39, v127
	v_mov_b32_e32 v38, v127
	v_mov_b32_e32 v37, v127
	v_mov_b32_e32 v36, v127
	v_mov_b32_e32 v35, v127
	v_mov_b32_e32 v34, v127
	v_mov_b32_e32 v33, v127
	v_mov_b32_e32 v32, v127
	v_mov_b32_e32 v23, v127
	v_mov_b32_e32 v22, v127
	v_mov_b32_e32 v21, v127
	v_mov_b32_e32 v20, v127
	v_mov_b32_e32 v19, v127
	v_mov_b32_e32 v18, v127
	v_mov_b32_e32 v17, v127
	v_mov_b32_e32 v16, v127
	v_mov_b32_e32 v7, v127
	v_mov_b32_e32 v6, v127
	v_mov_b32_e32 v5, v127
	v_mov_b32_e32 v4, v127
	v_mov_b32_e32 v3, v127
	v_mov_b32_e32 v2, v127
	v_mov_b32_e32 v1, v127
	v_mov_b32_e32 v0, v127
	s_branch .LBB0_324
.Lzskip_2:
	s_add_u32 s0, s52, 0x80
	s_addc_u32 s1, s53, 0
	s_add_u32 s33, s50, 0x100
	v_mov_b32_e32 v0, 0
	s_addc_u32 s52, s51, 0
	s_mov_b32 s50, 0
	v_mov_b32_e32 v1, v0
	v_mov_b32_e32 v2, v0
	v_mov_b32_e32 v3, v0
	v_mov_b32_e32 v4, v0
	v_mov_b32_e32 v5, v0
	v_mov_b32_e32 v6, v0
	v_mov_b32_e32 v7, v0
	v_mov_b32_e32 v16, v0
	v_mov_b32_e32 v17, v0
	v_mov_b32_e32 v18, v0
	v_mov_b32_e32 v19, v0
	v_mov_b32_e32 v20, v0
	v_mov_b32_e32 v21, v0
	v_mov_b32_e32 v22, v0
	v_mov_b32_e32 v23, v0
	v_mov_b32_e32 v32, v0
	v_mov_b32_e32 v33, v0
	v_mov_b32_e32 v34, v0
	v_mov_b32_e32 v35, v0
	v_mov_b32_e32 v36, v0
	v_mov_b32_e32 v37, v0
	v_mov_b32_e32 v38, v0
	v_mov_b32_e32 v39, v0
	v_mov_b32_e32 v48, v0
	v_mov_b32_e32 v49, v0
	v_mov_b32_e32 v50, v0
	v_mov_b32_e32 v51, v0
	v_mov_b32_e32 v52, v0
	v_mov_b32_e32 v53, v0
	v_mov_b32_e32 v54, v0
	v_mov_b32_e32 v55, v0
	v_mov_b32_e32 v8, v0
	v_mov_b32_e32 v9, v0
	v_mov_b32_e32 v10, v0
	v_mov_b32_e32 v11, v0
	v_mov_b32_e32 v12, v0
	v_mov_b32_e32 v13, v0
	v_mov_b32_e32 v14, v0
	v_mov_b32_e32 v15, v0
	v_mov_b32_e32 v24, v0
	v_mov_b32_e32 v25, v0
	v_mov_b32_e32 v26, v0
	v_mov_b32_e32 v27, v0
	v_mov_b32_e32 v28, v0
	v_mov_b32_e32 v29, v0
	v_mov_b32_e32 v30, v0
	v_mov_b32_e32 v31, v0
	v_mov_b32_e32 v40, v0
	v_mov_b32_e32 v41, v0
	v_mov_b32_e32 v42, v0
	v_mov_b32_e32 v43, v0
	v_mov_b32_e32 v44, v0
	v_mov_b32_e32 v45, v0
	v_mov_b32_e32 v46, v0
	v_mov_b32_e32 v47, v0
	v_mov_b32_e32 v56, v0
	v_mov_b32_e32 v57, v0
	v_mov_b32_e32 v58, v0
	v_mov_b32_e32 v59, v0
	v_mov_b32_e32 v60, v0
	v_mov_b32_e32 v61, v0
	v_mov_b32_e32 v62, v0
	v_mov_b32_e32 v63, v0
	v_mov_b32_e32 v64, v0
	v_mov_b32_e32 v65, v0
	v_mov_b32_e32 v66, v0
	v_mov_b32_e32 v67, v0
	v_mov_b32_e32 v68, v0
	v_mov_b32_e32 v69, v0
	v_mov_b32_e32 v70, v0
	v_mov_b32_e32 v71, v0
	v_mov_b32_e32 v80, v0
	v_mov_b32_e32 v81, v0
	v_mov_b32_e32 v82, v0
	v_mov_b32_e32 v83, v0
	v_mov_b32_e32 v84, v0
	v_mov_b32_e32 v85, v0
	v_mov_b32_e32 v86, v0
	v_mov_b32_e32 v87, v0
	v_mov_b32_e32 v96, v0
	v_mov_b32_e32 v97, v0
	v_mov_b32_e32 v98, v0
	v_mov_b32_e32 v99, v0
	v_mov_b32_e32 v100, v0
	v_mov_b32_e32 v101, v0
	v_mov_b32_e32 v102, v0
	v_mov_b32_e32 v103, v0
	v_mov_b32_e32 v112, v0
	v_mov_b32_e32 v113, v0
	v_mov_b32_e32 v114, v0
	v_mov_b32_e32 v115, v0
	v_mov_b32_e32 v116, v0
	v_mov_b32_e32 v117, v0
	v_mov_b32_e32 v118, v0
	v_mov_b32_e32 v119, v0
	v_mov_b32_e32 v72, v0
	v_mov_b32_e32 v73, v0
	v_mov_b32_e32 v74, v0
	v_mov_b32_e32 v75, v0
	v_mov_b32_e32 v76, v0
	v_mov_b32_e32 v77, v0
	v_mov_b32_e32 v78, v0
	v_mov_b32_e32 v79, v0
	v_mov_b32_e32 v88, v0
	v_mov_b32_e32 v89, v0
	v_mov_b32_e32 v90, v0
	v_mov_b32_e32 v91, v0
	v_mov_b32_e32 v92, v0
	v_mov_b32_e32 v93, v0
	v_mov_b32_e32 v94, v0
	v_mov_b32_e32 v95, v0
	v_mov_b32_e32 v104, v0
	v_mov_b32_e32 v105, v0
	v_mov_b32_e32 v106, v0
	v_mov_b32_e32 v107, v0
	v_mov_b32_e32 v108, v0
	v_mov_b32_e32 v109, v0
	v_mov_b32_e32 v110, v0
	v_mov_b32_e32 v111, v0
	v_mov_b32_e32 v120, v0
	v_mov_b32_e32 v121, v0
	v_mov_b32_e32 v122, v0
	v_mov_b32_e32 v123, v0
	v_mov_b32_e32 v124, v0
	v_mov_b32_e32 v125, v0
	v_mov_b32_e32 v126, v0
	v_mov_b32_e32 v127, v0

.LBB0_590:
	s_andn2_b64 vcc, exec, s[16:17]
	s_cbranch_vccz .Lzskip_3
	v_mov_b32_e32 v123, 0
	v_mov_b32_e32 v122, v123
	v_mov_b32_e32 v121, v123
	v_mov_b32_e32 v120, v123
	v_mov_b32_e32 v127, v123
	v_mov_b32_e32 v126, v123
	v_mov_b32_e32 v125, v123
	v_mov_b32_e32 v124, v123
	v_mov_b32_e32 v111, v123
	v_mov_b32_e32 v110, v123
	v_mov_b32_e32 v109, v123
	v_mov_b32_e32 v108, v123
	v_mov_b32_e32 v107, v123
	v_mov_b32_e32 v106, v123
	v_mov_b32_e32 v105, v123
	v_mov_b32_e32 v104, v123
	v_mov_b32_e32 v95, v123
	v_mov_b32_e32 v94, v123
	v_mov_b32_e32 v93, v123
	v_mov_b32_e32 v92, v123
	v_mov_b32_e32 v91, v123
	v_mov_b32_e32 v90, v123
	v_mov_b32_e32 v89, v123
	v_mov_b32_e32 v88, v123
	v_mov_b32_e32 v79, v123
	v_mov_b32_e32 v78, v123
	v_mov_b32_e32 v77, v123
	v_mov_b32_e32 v76, v123
	v_mov_b32_e32 v75, v123
	v_mov_b32_e32 v74, v123
	v_mov_b32_e32 v73, v123
	v_mov_b32_e32 v72, v123
	v_mov_b32_e32 v119, v123
	v_mov_b32_e32 v118, v123
	v_mov_b32_e32 v117, v123
	v_mov_b32_e32 v116, v123
	v_mov_b32_e32 v115, v123
	v_mov_b32_e32 v114, v123
	v_mov_b32_e32 v113, v123
	v_mov_b32_e32 v112, v123
	v_mov_b32_e32 v103, v123
	v_mov_b32_e32 v102, v123
	v_mov_b32_e32 v101, v123
	v_mov_b32_e32 v100, v123
	v_mov_b32_e32 v99, v123
	v_mov_b32_e32 v98, v123
	v_mov_b32_e32 v97, v123
	v_mov_b32_e32 v96, v123
	v_mov_b32_e32 v87, v123
	v_mov_b32_e32 v86, v123
	v_mov_b32_e32 v85, v123
	v_mov_b32_e32 v84, v123
	v_mov_b32_e32 v83, v123
	v_mov_b32_e32 v82, v123
	v_mov_b32_e32 v81, v123
	v_mov_b32_e32 v80, v123
	v_mov_b32_e32 v71, v123
	v_mov_b32_e32 v70, v123
	v_mov_b32_e32 v69, v123
	v_mov_b32_e32 v68, v123
	v_mov_b32_e32 v67, v123
	v_mov_b32_e32 v66, v123
	v_mov_b32_e32 v65, v123
	v_mov_b32_e32 v64, v123
	v_mov_b32_e32 v63, v123
	v_mov_b32_e32 v62, v123
	v_mov_b32_e32 v61, v123
	v_mov_b32_e32 v60, v123
	v_mov_b32_e32 v59, v123
	v_mov_b32_e32 v58, v123
	v_mov_b32_e32 v57, v123
	v_mov_b32_e32 v56, v123
	v_mov_b32_e32 v47, v123
	v_mov_b32_e32 v46, v123
	v_mov_b32_e32 v45, v123
	v_mov_b32_e32 v44, v123
	v_mov_b32_e32 v43, v123
	v_mov_b32_e32 v42, v123
	v_mov_b32_e32 v41, v123
	v_mov_b32_e32 v40, v123
	v_mov_b32_e32 v31, v123
	v_mov_b32_e32 v30, v123
	v_mov_b32_e32 v29, v123
	v_mov_b32_e32 v28, v123
	v_mov_b32_e32 v27, v123
	v_mov_b32_e32 v26, v123
	v_mov_b32_e32 v25, v123
	v_mov_b32_e32 v24, v123
	v_mov_b32_e32 v15, v123
	v_mov_b32_e32 v14, v123
	v_mov_b32_e32 v13, v123
	v_mov_b32_e32 v12, v123
	v_mov_b32_e32 v11, v123
	v_mov_b32_e32 v10, v123
	v_mov_b32_e32 v9, v123
	v_mov_b32_e32 v8, v123
	v_mov_b32_e32 v55, v123
	v_mov_b32_e32 v54, v123
	v_mov_b32_e32 v53, v123
	v_mov_b32_e32 v52, v123
	v_mov_b32_e32 v51, v123
	v_mov_b32_e32 v50, v123
	v_mov_b32_e32 v49, v123
	v_mov_b32_e32 v48, v123
	v_mov_b32_e32 v39, v123
	v_mov_b32_e32 v38, v123
	v_mov_b32_e32 v37, v123
	v_mov_b32_e32 v36, v123
	v_mov_b32_e32 v35, v123
	v_mov_b32_e32 v34, v123
	v_mov_b32_e32 v33, v123
	v_mov_b32_e32 v32, v123
	v_mov_b32_e32 v23, v123
	v_mov_b32_e32 v22, v123
	v_mov_b32_e32 v21, v123
	v_mov_b32_e32 v20, v123
	v_mov_b32_e32 v19, v123
	v_mov_b32_e32 v18, v123
	v_mov_b32_e32 v17, v123
	v_mov_b32_e32 v16, v123
	v_mov_b32_e32 v7, v123
	v_mov_b32_e32 v6, v123
	v_mov_b32_e32 v5, v123
	v_mov_b32_e32 v4, v123
	v_mov_b32_e32 v3, v123
	v_mov_b32_e32 v2, v123
	v_mov_b32_e32 v1, v123
	v_mov_b32_e32 v0, v123
	s_branch .LBB0_593
.Lzskip_3:
	s_add_u32 s30, s30, 0x80
	s_addc_u32 s31, s31, 0
	s_add_u32 s62, s34, 0x100
	v_mov_b32_e32 v0, 0
	s_addc_u32 s63, s35, 0
	s_mov_b32 s34, 0
	v_mov_b32_e32 v1, v0
	v_mov_b32_e32 v2, v0
	v_mov_b32_e32 v3, v0
	v_mov_b32_e32 v4, v0
	v_mov_b32_e32 v5, v0
	v_mov_b32_e32 v6, v0
	v_mov_b32_e32 v7, v0
	v_mov_b32_e32 v16, v0
	v_mov_b32_e32 v17, v0
	v_mov_b32_e32 v18, v0
	v_mov_b32_e32 v19, v0
	v_mov_b32_e32 v20, v0
	v_mov_b32_e32 v21, v0
	v_mov_b32_e32 v22, v0
	v_mov_b32_e32 v23, v0
	v_mov_b32_e32 v32, v0
	v_mov_b32_e32 v33, v0
	v_mov_b32_e32 v34, v0
	v_mov_b32_e32 v35, v0
	v_mov_b32_e32 v36, v0
	v_mov_b32_e32 v37, v0
	v_mov_b32_e32 v38, v0
	v_mov_b32_e32 v39, v0
	v_mov_b32_e32 v48, v0
	v_mov_b32_e32 v49, v0
	v_mov_b32_e32 v50, v0
	v_mov_b32_e32 v51, v0
	v_mov_b32_e32 v52, v0
	v_mov_b32_e32 v53, v0
	v_mov_b32_e32 v54, v0
	v_mov_b32_e32 v55, v0
	v_mov_b32_e32 v8, v0
	v_mov_b32_e32 v9, v0
	v_mov_b32_e32 v10, v0
	v_mov_b32_e32 v11, v0
	v_mov_b32_e32 v12, v0
	v_mov_b32_e32 v13, v0
	v_mov_b32_e32 v14, v0
	v_mov_b32_e32 v15, v0
	v_mov_b32_e32 v24, v0
	v_mov_b32_e32 v25, v0
	v_mov_b32_e32 v26, v0
	v_mov_b32_e32 v27, v0
	v_mov_b32_e32 v28, v0
	v_mov_b32_e32 v29, v0
	v_mov_b32_e32 v30, v0
	v_mov_b32_e32 v31, v0
	v_mov_b32_e32 v40, v0
	v_mov_b32_e32 v41, v0
	v_mov_b32_e32 v42, v0
	v_mov_b32_e32 v43, v0
	v_mov_b32_e32 v44, v0
	v_mov_b32_e32 v45, v0
	v_mov_b32_e32 v46, v0
	v_mov_b32_e32 v47, v0
	v_mov_b32_e32 v56, v0
	v_mov_b32_e32 v57, v0
	v_mov_b32_e32 v58, v0
	v_mov_b32_e32 v59, v0
	v_mov_b32_e32 v60, v0
	v_mov_b32_e32 v61, v0
	v_mov_b32_e32 v62, v0
	v_mov_b32_e32 v63, v0
	v_mov_b32_e32 v64, v0
	v_mov_b32_e32 v65, v0
	v_mov_b32_e32 v66, v0
	v_mov_b32_e32 v67, v0
	v_mov_b32_e32 v68, v0
	v_mov_b32_e32 v69, v0
	v_mov_b32_e32 v70, v0
	v_mov_b32_e32 v71, v0
	v_mov_b32_e32 v80, v0
	v_mov_b32_e32 v81, v0
	v_mov_b32_e32 v82, v0
	v_mov_b32_e32 v83, v0
	v_mov_b32_e32 v84, v0
	v_mov_b32_e32 v85, v0
	v_mov_b32_e32 v86, v0
	v_mov_b32_e32 v87, v0
	v_mov_b32_e32 v96, v0
	v_mov_b32_e32 v97, v0
	v_mov_b32_e32 v98, v0
	v_mov_b32_e32 v99, v0
	v_mov_b32_e32 v100, v0
	v_mov_b32_e32 v101, v0
	v_mov_b32_e32 v102, v0
	v_mov_b32_e32 v103, v0
	v_mov_b32_e32 v112, v0
	v_mov_b32_e32 v113, v0
	v_mov_b32_e32 v114, v0
	v_mov_b32_e32 v115, v0
	v_mov_b32_e32 v116, v0
	v_mov_b32_e32 v117, v0
	v_mov_b32_e32 v118, v0
	v_mov_b32_e32 v119, v0
	v_mov_b32_e32 v72, v0
	v_mov_b32_e32 v73, v0
	v_mov_b32_e32 v74, v0
	v_mov_b32_e32 v75, v0
	v_mov_b32_e32 v76, v0
	v_mov_b32_e32 v77, v0
	v_mov_b32_e32 v78, v0
	v_mov_b32_e32 v79, v0
	v_mov_b32_e32 v88, v0
	v_mov_b32_e32 v89, v0
	v_mov_b32_e32 v90, v0
	v_mov_b32_e32 v91, v0
	v_mov_b32_e32 v92, v0
	v_mov_b32_e32 v93, v0
	v_mov_b32_e32 v94, v0
	v_mov_b32_e32 v95, v0
	v_mov_b32_e32 v104, v0
	v_mov_b32_e32 v105, v0
	v_mov_b32_e32 v106, v0
	v_mov_b32_e32 v107, v0
	v_mov_b32_e32 v108, v0
	v_mov_b32_e32 v109, v0
	v_mov_b32_e32 v110, v0
	v_mov_b32_e32 v111, v0
	v_mov_b32_e32 v124, v0
	v_mov_b32_e32 v125, v0
	v_mov_b32_e32 v126, v0
	v_mov_b32_e32 v127, v0
	v_mov_b32_e32 v120, v0
	v_mov_b32_e32 v121, v0
	v_mov_b32_e32 v122, v0
	v_mov_b32_e32 v123, v0

.LBB0_761:
	s_andn2_b64 vcc, exec, s[18:19]
	s_cbranch_vccz .Lzskip_4
	v_mov_b32_e32 v123, 0
	v_mov_b32_e32 v122, v123
	v_mov_b32_e32 v121, v123
	v_mov_b32_e32 v120, v123
	v_mov_b32_e32 v127, v123
	v_mov_b32_e32 v126, v123
	v_mov_b32_e32 v125, v123
	v_mov_b32_e32 v124, v123
	v_mov_b32_e32 v111, v123
	v_mov_b32_e32 v110, v123
	v_mov_b32_e32 v109, v123
	v_mov_b32_e32 v108, v123
	v_mov_b32_e32 v107, v123
	v_mov_b32_e32 v106, v123
	v_mov_b32_e32 v105, v123
	v_mov_b32_e32 v104, v123
	v_mov_b32_e32 v95, v123
	v_mov_b32_e32 v94, v123
	v_mov_b32_e32 v93, v123
	v_mov_b32_e32 v92, v123
	v_mov_b32_e32 v91, v123
	v_mov_b32_e32 v90, v123
	v_mov_b32_e32 v89, v123
	v_mov_b32_e32 v88, v123
	v_mov_b32_e32 v79, v123
	v_mov_b32_e32 v78, v123
	v_mov_b32_e32 v77, v123
	v_mov_b32_e32 v76, v123
	v_mov_b32_e32 v75, v123
	v_mov_b32_e32 v74, v123
	v_mov_b32_e32 v73, v123
	v_mov_b32_e32 v72, v123
	v_mov_b32_e32 v119, v123
	v_mov_b32_e32 v118, v123
	v_mov_b32_e32 v117, v123
	v_mov_b32_e32 v116, v123
	v_mov_b32_e32 v115, v123
	v_mov_b32_e32 v114, v123
	v_mov_b32_e32 v113, v123
	v_mov_b32_e32 v112, v123
	v_mov_b32_e32 v103, v123
	v_mov_b32_e32 v102, v123
	v_mov_b32_e32 v101, v123
	v_mov_b32_e32 v100, v123
	v_mov_b32_e32 v99, v123
	v_mov_b32_e32 v98, v123
	v_mov_b32_e32 v97, v123
	v_mov_b32_e32 v96, v123
	v_mov_b32_e32 v87, v123
	v_mov_b32_e32 v86, v123
	v_mov_b32_e32 v85, v123
	v_mov_b32_e32 v84, v123
	v_mov_b32_e32 v83, v123
	v_mov_b32_e32 v82, v123
	v_mov_b32_e32 v81, v123
	v_mov_b32_e32 v80, v123
	v_mov_b32_e32 v71, v123
	v_mov_b32_e32 v70, v123
	v_mov_b32_e32 v69, v123
	v_mov_b32_e32 v68, v123
	v_mov_b32_e32 v67, v123
	v_mov_b32_e32 v66, v123
	v_mov_b32_e32 v65, v123
	v_mov_b32_e32 v64, v123
	v_mov_b32_e32 v63, v123
	v_mov_b32_e32 v62, v123
	v_mov_b32_e32 v61, v123
	v_mov_b32_e32 v60, v123
	v_mov_b32_e32 v59, v123
	v_mov_b32_e32 v58, v123
	v_mov_b32_e32 v57, v123
	v_mov_b32_e32 v56, v123
	v_mov_b32_e32 v47, v123
	v_mov_b32_e32 v46, v123
	v_mov_b32_e32 v45, v123
	v_mov_b32_e32 v44, v123
	v_mov_b32_e32 v43, v123
	v_mov_b32_e32 v42, v123
	v_mov_b32_e32 v41, v123
	v_mov_b32_e32 v40, v123
	v_mov_b32_e32 v31, v123
	v_mov_b32_e32 v30, v123
	v_mov_b32_e32 v29, v123
	v_mov_b32_e32 v28, v123
	v_mov_b32_e32 v27, v123
	v_mov_b32_e32 v26, v123
	v_mov_b32_e32 v25, v123
	v_mov_b32_e32 v24, v123
	v_mov_b32_e32 v15, v123
	v_mov_b32_e32 v14, v123
	v_mov_b32_e32 v13, v123
	v_mov_b32_e32 v12, v123
	v_mov_b32_e32 v11, v123
	v_mov_b32_e32 v10, v123
	v_mov_b32_e32 v9, v123
	v_mov_b32_e32 v8, v123
	v_mov_b32_e32 v55, v123
	v_mov_b32_e32 v54, v123
	v_mov_b32_e32 v53, v123
	v_mov_b32_e32 v52, v123
	v_mov_b32_e32 v51, v123
	v_mov_b32_e32 v50, v123
	v_mov_b32_e32 v49, v123
	v_mov_b32_e32 v48, v123
	v_mov_b32_e32 v39, v123
	v_mov_b32_e32 v38, v123
	v_mov_b32_e32 v37, v123
	v_mov_b32_e32 v36, v123
	v_mov_b32_e32 v35, v123
	v_mov_b32_e32 v34, v123
	v_mov_b32_e32 v33, v123
	v_mov_b32_e32 v32, v123
	v_mov_b32_e32 v23, v123
	v_mov_b32_e32 v22, v123
	v_mov_b32_e32 v21, v123
	v_mov_b32_e32 v20, v123
	v_mov_b32_e32 v19, v123
	v_mov_b32_e32 v18, v123
	v_mov_b32_e32 v17, v123
	v_mov_b32_e32 v16, v123
	v_mov_b32_e32 v7, v123
	v_mov_b32_e32 v6, v123
	v_mov_b32_e32 v5, v123
	v_mov_b32_e32 v4, v123
	v_mov_b32_e32 v3, v123
	v_mov_b32_e32 v2, v123
	v_mov_b32_e32 v1, v123
	v_mov_b32_e32 v0, v123
	s_branch .LBB0_764
.Lzskip_4:
	s_add_u32 s24, s24, 0x80
	s_addc_u32 s25, s25, 0
	s_add_u32 s52, s26, 0x100
	v_mov_b32_e32 v0, 0
	s_addc_u32 s53, s27, 0
	s_mov_b32 s26, 0
	v_mov_b32_e32 v1, v0
	v_mov_b32_e32 v2, v0
	v_mov_b32_e32 v3, v0
	v_mov_b32_e32 v4, v0
	v_mov_b32_e32 v5, v0
	v_mov_b32_e32 v6, v0
	v_mov_b32_e32 v7, v0
	v_mov_b32_e32 v16, v0
	v_mov_b32_e32 v17, v0
	v_mov_b32_e32 v18, v0
	v_mov_b32_e32 v19, v0
	v_mov_b32_e32 v20, v0
	v_mov_b32_e32 v21, v0
	v_mov_b32_e32 v22, v0
	v_mov_b32_e32 v23, v0
	v_mov_b32_e32 v32, v0
	v_mov_b32_e32 v33, v0
	v_mov_b32_e32 v34, v0
	v_mov_b32_e32 v35, v0
	v_mov_b32_e32 v36, v0
	v_mov_b32_e32 v37, v0
	v_mov_b32_e32 v38, v0
	v_mov_b32_e32 v39, v0
	v_mov_b32_e32 v48, v0
	v_mov_b32_e32 v49, v0
	v_mov_b32_e32 v50, v0
	v_mov_b32_e32 v51, v0
	v_mov_b32_e32 v52, v0
	v_mov_b32_e32 v53, v0
	v_mov_b32_e32 v54, v0
	v_mov_b32_e32 v55, v0
	v_mov_b32_e32 v8, v0
	v_mov_b32_e32 v9, v0
	v_mov_b32_e32 v10, v0
	v_mov_b32_e32 v11, v0
	v_mov_b32_e32 v12, v0
	v_mov_b32_e32 v13, v0
	v_mov_b32_e32 v14, v0
	v_mov_b32_e32 v15, v0
	v_mov_b32_e32 v24, v0
	v_mov_b32_e32 v25, v0
	v_mov_b32_e32 v26, v0
	v_mov_b32_e32 v27, v0
	v_mov_b32_e32 v28, v0
	v_mov_b32_e32 v29, v0
	v_mov_b32_e32 v30, v0
	v_mov_b32_e32 v31, v0
	v_mov_b32_e32 v40, v0
	v_mov_b32_e32 v41, v0
	v_mov_b32_e32 v42, v0
	v_mov_b32_e32 v43, v0
	v_mov_b32_e32 v44, v0
	v_mov_b32_e32 v45, v0
	v_mov_b32_e32 v46, v0
	v_mov_b32_e32 v47, v0
	v_mov_b32_e32 v56, v0
	v_mov_b32_e32 v57, v0
	v_mov_b32_e32 v58, v0
	v_mov_b32_e32 v59, v0
	v_mov_b32_e32 v60, v0
	v_mov_b32_e32 v61, v0
	v_mov_b32_e32 v62, v0
	v_mov_b32_e32 v63, v0
	v_mov_b32_e32 v64, v0
	v_mov_b32_e32 v65, v0
	v_mov_b32_e32 v66, v0
	v_mov_b32_e32 v67, v0
	v_mov_b32_e32 v68, v0
	v_mov_b32_e32 v69, v0
	v_mov_b32_e32 v70, v0
	v_mov_b32_e32 v71, v0
	v_mov_b32_e32 v80, v0
	v_mov_b32_e32 v81, v0
	v_mov_b32_e32 v82, v0
	v_mov_b32_e32 v83, v0
	v_mov_b32_e32 v84, v0
	v_mov_b32_e32 v85, v0
	v_mov_b32_e32 v86, v0
	v_mov_b32_e32 v87, v0
	v_mov_b32_e32 v96, v0
	v_mov_b32_e32 v97, v0
	v_mov_b32_e32 v98, v0
	v_mov_b32_e32 v99, v0
	v_mov_b32_e32 v100, v0
	v_mov_b32_e32 v101, v0
	v_mov_b32_e32 v102, v0
	v_mov_b32_e32 v103, v0
	v_mov_b32_e32 v112, v0
	v_mov_b32_e32 v113, v0
	v_mov_b32_e32 v114, v0
	v_mov_b32_e32 v115, v0
	v_mov_b32_e32 v116, v0
	v_mov_b32_e32 v117, v0
	v_mov_b32_e32 v118, v0
	v_mov_b32_e32 v119, v0
	v_mov_b32_e32 v72, v0
	v_mov_b32_e32 v73, v0
	v_mov_b32_e32 v74, v0
	v_mov_b32_e32 v75, v0
	v_mov_b32_e32 v76, v0
	v_mov_b32_e32 v77, v0
	v_mov_b32_e32 v78, v0
	v_mov_b32_e32 v79, v0
	v_mov_b32_e32 v88, v0
	v_mov_b32_e32 v89, v0
	v_mov_b32_e32 v90, v0
	v_mov_b32_e32 v91, v0
	v_mov_b32_e32 v92, v0
	v_mov_b32_e32 v93, v0
	v_mov_b32_e32 v94, v0
	v_mov_b32_e32 v95, v0
	v_mov_b32_e32 v104, v0
	v_mov_b32_e32 v105, v0
	v_mov_b32_e32 v106, v0
	v_mov_b32_e32 v107, v0
	v_mov_b32_e32 v108, v0
	v_mov_b32_e32 v109, v0
	v_mov_b32_e32 v110, v0
	v_mov_b32_e32 v111, v0
	v_mov_b32_e32 v124, v0
	v_mov_b32_e32 v125, v0
	v_mov_b32_e32 v126, v0
	v_mov_b32_e32 v127, v0
	v_mov_b32_e32 v120, v0
	v_mov_b32_e32 v121, v0
	v_mov_b32_e32 v122, v0
	v_mov_b32_e32 v123, v0

.LBB0_847:
	s_andn2_b64 vcc, exec, s[20:21]
	s_waitcnt lgkmcnt(0)
	s_cbranch_vccz .Lzskip_5
	v_mov_b32_e32 v139, 0
	v_mov_b32_e32 v138, v139
	v_mov_b32_e32 v137, v139
	v_mov_b32_e32 v136, v139
	v_mov_b32_e32 v143, v139
	v_mov_b32_e32 v142, v139
	v_mov_b32_e32 v141, v139
	v_mov_b32_e32 v140, v139
	v_mov_b32_e32 v111, v139
	v_mov_b32_e32 v110, v139
	v_mov_b32_e32 v109, v139
	v_mov_b32_e32 v108, v139
	v_mov_b32_e32 v107, v139
	v_mov_b32_e32 v106, v139
	v_mov_b32_e32 v105, v139
	v_mov_b32_e32 v104, v139
	v_mov_b32_e32 v95, v139
	v_mov_b32_e32 v94, v139
	v_mov_b32_e32 v93, v139
	v_mov_b32_e32 v92, v139
	v_mov_b32_e32 v91, v139
	v_mov_b32_e32 v90, v139
	v_mov_b32_e32 v89, v139
	v_mov_b32_e32 v88, v139
	v_mov_b32_e32 v79, v139
	v_mov_b32_e32 v78, v139
	v_mov_b32_e32 v77, v139
	v_mov_b32_e32 v76, v139
	v_mov_b32_e32 v75, v139
	v_mov_b32_e32 v74, v139
	v_mov_b32_e32 v73, v139
	v_mov_b32_e32 v72, v139
	v_mov_b32_e32 v135, v139
	v_mov_b32_e32 v134, v139
	v_mov_b32_e32 v133, v139
	v_mov_b32_e32 v132, v139
	v_mov_b32_e32 v127, v139
	v_mov_b32_e32 v126, v139
	v_mov_b32_e32 v125, v139
	v_mov_b32_e32 v124, v139
	v_mov_b32_e32 v103, v139
	v_mov_b32_e32 v102, v139
	v_mov_b32_e32 v101, v139
	v_mov_b32_e32 v100, v139
	v_mov_b32_e32 v99, v139
	v_mov_b32_e32 v98, v139
	v_mov_b32_e32 v97, v139
	v_mov_b32_e32 v96, v139
	v_mov_b32_e32 v87, v139
	v_mov_b32_e32 v86, v139
	v_mov_b32_e32 v85, v139
	v_mov_b32_e32 v84, v139
	v_mov_b32_e32 v83, v139
	v_mov_b32_e32 v82, v139
	v_mov_b32_e32 v81, v139
	v_mov_b32_e32 v80, v139
	v_mov_b32_e32 v71, v139
	v_mov_b32_e32 v70, v139
	v_mov_b32_e32 v69, v139
	v_mov_b32_e32 v68, v139
	v_mov_b32_e32 v67, v139
	v_mov_b32_e32 v66, v139
	v_mov_b32_e32 v65, v139
	v_mov_b32_e32 v64, v139
	v_mov_b32_e32 v63, v139
	v_mov_b32_e32 v62, v139
	v_mov_b32_e32 v61, v139
	v_mov_b32_e32 v60, v139
	v_mov_b32_e32 v59, v139
	v_mov_b32_e32 v58, v139
	v_mov_b32_e32 v57, v139
	v_mov_b32_e32 v56, v139
	v_mov_b32_e32 v47, v139
	v_mov_b32_e32 v46, v139
	v_mov_b32_e32 v45, v139
	v_mov_b32_e32 v44, v139
	v_mov_b32_e32 v43, v139
	v_mov_b32_e32 v42, v139
	v_mov_b32_e32 v41, v139
	v_mov_b32_e32 v40, v139
	v_mov_b32_e32 v31, v139
	v_mov_b32_e32 v30, v139
	v_mov_b32_e32 v29, v139
	v_mov_b32_e32 v28, v139
	v_mov_b32_e32 v27, v139
	v_mov_b32_e32 v26, v139
	v_mov_b32_e32 v25, v139
	v_mov_b32_e32 v24, v139
	v_mov_b32_e32 v15, v139
	v_mov_b32_e32 v14, v139
	v_mov_b32_e32 v13, v139
	v_mov_b32_e32 v12, v139
	v_mov_b32_e32 v11, v139
	v_mov_b32_e32 v10, v139
	v_mov_b32_e32 v9, v139
	v_mov_b32_e32 v8, v139
	v_mov_b32_e32 v55, v139
	v_mov_b32_e32 v54, v139
	v_mov_b32_e32 v53, v139
	v_mov_b32_e32 v52, v139
	v_mov_b32_e32 v51, v139
	v_mov_b32_e32 v50, v139
	v_mov_b32_e32 v49, v139
	v_mov_b32_e32 v48, v139
	v_mov_b32_e32 v39, v139
	v_mov_b32_e32 v38, v139
	v_mov_b32_e32 v37, v139
	v_mov_b32_e32 v36, v139
	v_mov_b32_e32 v35, v139
	v_mov_b32_e32 v34, v139
	v_mov_b32_e32 v33, v139
	v_mov_b32_e32 v32, v139
	v_mov_b32_e32 v23, v139
	v_mov_b32_e32 v22, v139
	v_mov_b32_e32 v21, v139
	v_mov_b32_e32 v20, v139
	v_mov_b32_e32 v19, v139
	v_mov_b32_e32 v18, v139
	v_mov_b32_e32 v17, v139
	v_mov_b32_e32 v16, v139
	v_mov_b32_e32 v7, v139
	v_mov_b32_e32 v6, v139
	v_mov_b32_e32 v5, v139
	v_mov_b32_e32 v4, v139
	v_mov_b32_e32 v3, v139
	v_mov_b32_e32 v2, v139
	v_mov_b32_e32 v1, v139
	v_mov_b32_e32 v0, v139
	s_branch .LBB0_850
.Lzskip_5:
	s_add_u32 s28, s28, 0x80
	s_addc_u32 s29, s29, 0
	s_add_u32 s60, s30, 0x100
	v_mov_b32_e32 v0, 0
	s_addc_u32 s61, s31, 0
	s_mov_b32 s30, 0
	v_mov_b32_e32 v1, v0
	v_mov_b32_e32 v2, v0
	v_mov_b32_e32 v3, v0
	v_mov_b32_e32 v4, v0
	v_mov_b32_e32 v5, v0
	v_mov_b32_e32 v6, v0
	v_mov_b32_e32 v7, v0
	v_mov_b32_e32 v16, v0
	v_mov_b32_e32 v17, v0
	v_mov_b32_e32 v18, v0
	v_mov_b32_e32 v19, v0
	v_mov_b32_e32 v20, v0
	v_mov_b32_e32 v21, v0
	v_mov_b32_e32 v22, v0
	v_mov_b32_e32 v23, v0
	v_mov_b32_e32 v32, v0
	v_mov_b32_e32 v33, v0
	v_mov_b32_e32 v34, v0
	v_mov_b32_e32 v35, v0
	v_mov_b32_e32 v36, v0
	v_mov_b32_e32 v37, v0
	v_mov_b32_e32 v38, v0
	v_mov_b32_e32 v39, v0
	v_mov_b32_e32 v48, v0
	v_mov_b32_e32 v49, v0
	v_mov_b32_e32 v50, v0
	v_mov_b32_e32 v51, v0
	v_mov_b32_e32 v52, v0
	v_mov_b32_e32 v53, v0
	v_mov_b32_e32 v54, v0
	v_mov_b32_e32 v55, v0
	v_mov_b32_e32 v8, v0
	v_mov_b32_e32 v9, v0
	v_mov_b32_e32 v10, v0
	v_mov_b32_e32 v11, v0
	v_mov_b32_e32 v12, v0
	v_mov_b32_e32 v13, v0
	v_mov_b32_e32 v14, v0
	v_mov_b32_e32 v15, v0
	v_mov_b32_e32 v24, v0
	v_mov_b32_e32 v25, v0
	v_mov_b32_e32 v26, v0
	v_mov_b32_e32 v27, v0
	v_mov_b32_e32 v28, v0
	v_mov_b32_e32 v29, v0
	v_mov_b32_e32 v30, v0
	v_mov_b32_e32 v31, v0
	v_mov_b32_e32 v40, v0
	v_mov_b32_e32 v41, v0
	v_mov_b32_e32 v42, v0
	v_mov_b32_e32 v43, v0
	v_mov_b32_e32 v44, v0
	v_mov_b32_e32 v45, v0
	v_mov_b32_e32 v46, v0
	v_mov_b32_e32 v47, v0
	v_mov_b32_e32 v56, v0
	v_mov_b32_e32 v57, v0
	v_mov_b32_e32 v58, v0
	v_mov_b32_e32 v59, v0
	v_mov_b32_e32 v60, v0
	v_mov_b32_e32 v61, v0
	v_mov_b32_e32 v62, v0
	v_mov_b32_e32 v63, v0
	v_mov_b32_e32 v64, v0
	v_mov_b32_e32 v65, v0
	v_mov_b32_e32 v66, v0
	v_mov_b32_e32 v67, v0
	v_mov_b32_e32 v68, v0
	v_mov_b32_e32 v69, v0
	v_mov_b32_e32 v70, v0
	v_mov_b32_e32 v71, v0
	v_mov_b32_e32 v80, v0
	v_mov_b32_e32 v81, v0
	v_mov_b32_e32 v82, v0
	v_mov_b32_e32 v83, v0
	v_mov_b32_e32 v84, v0
	v_mov_b32_e32 v85, v0
	v_mov_b32_e32 v86, v0
	v_mov_b32_e32 v87, v0
	v_mov_b32_e32 v96, v0
	v_mov_b32_e32 v97, v0
	v_mov_b32_e32 v98, v0
	v_mov_b32_e32 v99, v0
	v_mov_b32_e32 v100, v0
	v_mov_b32_e32 v101, v0
	v_mov_b32_e32 v102, v0
	v_mov_b32_e32 v103, v0
	v_mov_b32_e32 v124, v0
	v_mov_b32_e32 v125, v0
	v_mov_b32_e32 v126, v0
	v_mov_b32_e32 v127, v0
	v_mov_b32_e32 v132, v0
	v_mov_b32_e32 v133, v0
	v_mov_b32_e32 v134, v0
	v_mov_b32_e32 v135, v0
	v_mov_b32_e32 v72, v0
	v_mov_b32_e32 v73, v0
	v_mov_b32_e32 v74, v0
	v_mov_b32_e32 v75, v0
	v_mov_b32_e32 v76, v0
	v_mov_b32_e32 v77, v0
	v_mov_b32_e32 v78, v0
	v_mov_b32_e32 v79, v0
	v_mov_b32_e32 v88, v0
	v_mov_b32_e32 v89, v0
	v_mov_b32_e32 v90, v0
	v_mov_b32_e32 v91, v0
	v_mov_b32_e32 v92, v0
	v_mov_b32_e32 v93, v0
	v_mov_b32_e32 v94, v0
	v_mov_b32_e32 v95, v0
	v_mov_b32_e32 v104, v0
	v_mov_b32_e32 v105, v0
	v_mov_b32_e32 v106, v0
	v_mov_b32_e32 v107, v0
	v_mov_b32_e32 v108, v0
	v_mov_b32_e32 v109, v0
	v_mov_b32_e32 v110, v0
	v_mov_b32_e32 v111, v0
	v_mov_b32_e32 v140, v0
	v_mov_b32_e32 v141, v0
	v_mov_b32_e32 v142, v0
	v_mov_b32_e32 v143, v0
	v_mov_b32_e32 v136, v0
	v_mov_b32_e32 v137, v0
	v_mov_b32_e32 v138, v0
	v_mov_b32_e32 v139, v0

.Lzskip_6:
	s_add_u32 s30, s30, 0x80
	s_addc_u32 s31, s31, 0
	s_add_u32 s66, s34, 0x100
	v_mov_b32_e32 v0, 0
	s_addc_u32 s67, s35, 0
	s_mov_b32 s34, 0
	v_mov_b32_e32 v1, v0
	v_mov_b32_e32 v2, v0
	v_mov_b32_e32 v3, v0
	v_mov_b32_e32 v4, v0
	v_mov_b32_e32 v5, v0
	v_mov_b32_e32 v6, v0
	v_mov_b32_e32 v7, v0
	v_mov_b32_e32 v16, v0
	v_mov_b32_e32 v17, v0
	v_mov_b32_e32 v18, v0
	v_mov_b32_e32 v19, v0
	v_mov_b32_e32 v20, v0
	v_mov_b32_e32 v21, v0
	v_mov_b32_e32 v22, v0
	v_mov_b32_e32 v23, v0
	v_mov_b32_e32 v32, v0
	v_mov_b32_e32 v33, v0
	v_mov_b32_e32 v34, v0
	v_mov_b32_e32 v35, v0
	v_mov_b32_e32 v36, v0
	v_mov_b32_e32 v37, v0
	v_mov_b32_e32 v38, v0
	v_mov_b32_e32 v39, v0
	v_mov_b32_e32 v48, v0
	v_mov_b32_e32 v49, v0
	v_mov_b32_e32 v50, v0
	v_mov_b32_e32 v51, v0
	v_mov_b32_e32 v52, v0
	v_mov_b32_e32 v53, v0
	v_mov_b32_e32 v54, v0
	v_mov_b32_e32 v55, v0
	v_mov_b32_e32 v8, v0
	v_mov_b32_e32 v9, v0
	v_mov_b32_e32 v10, v0
	v_mov_b32_e32 v11, v0
	v_mov_b32_e32 v12, v0
	v_mov_b32_e32 v13, v0
	v_mov_b32_e32 v14, v0
	v_mov_b32_e32 v15, v0
	v_mov_b32_e32 v24, v0
	v_mov_b32_e32 v25, v0
	v_mov_b32_e32 v26, v0
	v_mov_b32_e32 v27, v0
	v_mov_b32_e32 v28, v0
	v_mov_b32_e32 v29, v0
	v_mov_b32_e32 v30, v0
	v_mov_b32_e32 v31, v0
	v_mov_b32_e32 v40, v0
	v_mov_b32_e32 v41, v0
	v_mov_b32_e32 v42, v0
	v_mov_b32_e32 v43, v0
	v_mov_b32_e32 v44, v0
	v_mov_b32_e32 v45, v0
	v_mov_b32_e32 v46, v0
	v_mov_b32_e32 v47, v0
	v_mov_b32_e32 v56, v0
	v_mov_b32_e32 v57, v0
	v_mov_b32_e32 v58, v0
	v_mov_b32_e32 v59, v0
	v_mov_b32_e32 v60, v0
	v_mov_b32_e32 v61, v0
	v_mov_b32_e32 v62, v0
	v_mov_b32_e32 v63, v0
	v_mov_b32_e32 v64, v0
	v_mov_b32_e32 v65, v0
	v_mov_b32_e32 v66, v0
	v_mov_b32_e32 v67, v0
	v_mov_b32_e32 v68, v0
	v_mov_b32_e32 v69, v0
	v_mov_b32_e32 v70, v0
	v_mov_b32_e32 v71, v0
	v_mov_b32_e32 v80, v0
	v_mov_b32_e32 v81, v0
	v_mov_b32_e32 v82, v0
	v_mov_b32_e32 v83, v0
	v_mov_b32_e32 v84, v0
	v_mov_b32_e32 v85, v0
	v_mov_b32_e32 v86, v0
	v_mov_b32_e32 v87, v0
	v_mov_b32_e32 v96, v0
	v_mov_b32_e32 v97, v0
	v_mov_b32_e32 v98, v0
	v_mov_b32_e32 v99, v0
	v_mov_b32_e32 v100, v0
	v_mov_b32_e32 v101, v0
	v_mov_b32_e32 v102, v0
	v_mov_b32_e32 v103, v0
	v_mov_b32_e32 v112, v0
	v_mov_b32_e32 v113, v0
	v_mov_b32_e32 v114, v0
	v_mov_b32_e32 v115, v0
	v_mov_b32_e32 v116, v0
	v_mov_b32_e32 v117, v0
	v_mov_b32_e32 v118, v0
	v_mov_b32_e32 v119, v0
	v_mov_b32_e32 v72, v0
	v_mov_b32_e32 v73, v0
	v_mov_b32_e32 v74, v0
	v_mov_b32_e32 v75, v0
	v_mov_b32_e32 v76, v0
	v_mov_b32_e32 v77, v0
	v_mov_b32_e32 v78, v0
	v_mov_b32_e32 v79, v0
	v_mov_b32_e32 v88, v0
	v_mov_b32_e32 v89, v0
	v_mov_b32_e32 v90, v0
	v_mov_b32_e32 v91, v0
	v_mov_b32_e32 v92, v0
	v_mov_b32_e32 v93, v0
	v_mov_b32_e32 v94, v0
	v_mov_b32_e32 v95, v0
	v_mov_b32_e32 v104, v0
	v_mov_b32_e32 v105, v0
	v_mov_b32_e32 v106, v0
	v_mov_b32_e32 v107, v0
	v_mov_b32_e32 v108, v0
	v_mov_b32_e32 v109, v0
	v_mov_b32_e32 v110, v0
	v_mov_b32_e32 v111, v0
	v_mov_b32_e32 v124, v0
	v_mov_b32_e32 v125, v0
	v_mov_b32_e32 v126, v0
	v_mov_b32_e32 v127, v0
	v_mov_b32_e32 v120, v0
	v_mov_b32_e32 v121, v0
	v_mov_b32_e32 v122, v0
	v_mov_b32_e32 v123, v0

.LBB0_968:
	s_andn2_b64 vcc, exec, s[26:27]
	s_cbranch_vccz .Lzskip_7
	v_mov_b32_e32 v127, 0
	v_mov_b32_e32 v126, v127
	v_mov_b32_e32 v125, v127
	v_mov_b32_e32 v124, v127
	v_mov_b32_e32 v123, v127
	v_mov_b32_e32 v122, v127
	v_mov_b32_e32 v121, v127
	v_mov_b32_e32 v120, v127
	v_mov_b32_e32 v111, v127
	v_mov_b32_e32 v110, v127
	v_mov_b32_e32 v109, v127
	v_mov_b32_e32 v108, v127
	v_mov_b32_e32 v107, v127
	v_mov_b32_e32 v106, v127
	v_mov_b32_e32 v105, v127
	v_mov_b32_e32 v104, v127
	v_mov_b32_e32 v95, v127
	v_mov_b32_e32 v94, v127
	v_mov_b32_e32 v93, v127
	v_mov_b32_e32 v92, v127
	v_mov_b32_e32 v91, v127
	v_mov_b32_e32 v90, v127
	v_mov_b32_e32 v89, v127
	v_mov_b32_e32 v88, v127
	v_mov_b32_e32 v79, v127
	v_mov_b32_e32 v78, v127
	v_mov_b32_e32 v77, v127
	v_mov_b32_e32 v76, v127
	v_mov_b32_e32 v75, v127
	v_mov_b32_e32 v74, v127
	v_mov_b32_e32 v73, v127
	v_mov_b32_e32 v72, v127
	v_mov_b32_e32 v119, v127
	v_mov_b32_e32 v118, v127
	v_mov_b32_e32 v117, v127
	v_mov_b32_e32 v116, v127
	v_mov_b32_e32 v115, v127
	v_mov_b32_e32 v114, v127
	v_mov_b32_e32 v113, v127
	v_mov_b32_e32 v112, v127
	v_mov_b32_e32 v103, v127
	v_mov_b32_e32 v102, v127
	v_mov_b32_e32 v101, v127
	v_mov_b32_e32 v100, v127
	v_mov_b32_e32 v99, v127
	v_mov_b32_e32 v98, v127
	v_mov_b32_e32 v97, v127
	v_mov_b32_e32 v96, v127
	v_mov_b32_e32 v87, v127
	v_mov_b32_e32 v86, v127
	v_mov_b32_e32 v85, v127
	v_mov_b32_e32 v84, v127
	v_mov_b32_e32 v83, v127
	v_mov_b32_e32 v82, v127
	v_mov_b32_e32 v81, v127
	v_mov_b32_e32 v80, v127
	v_mov_b32_e32 v71, v127
	v_mov_b32_e32 v70, v127
	v_mov_b32_e32 v69, v127
	v_mov_b32_e32 v68, v127
	v_mov_b32_e32 v67, v127
	v_mov_b32_e32 v66, v127
	v_mov_b32_e32 v65, v127
	v_mov_b32_e32 v64, v127
	v_mov_b32_e32 v63, v127
	v_mov_b32_e32 v62, v127
	v_mov_b32_e32 v61, v127
	v_mov_b32_e32 v60, v127
	v_mov_b32_e32 v59, v127
	v_mov_b32_e32 v58, v127
	v_mov_b32_e32 v57, v127
	v_mov_b32_e32 v56, v127
	v_mov_b32_e32 v47, v127
	v_mov_b32_e32 v46, v127
	v_mov_b32_e32 v45, v127
	v_mov_b32_e32 v44, v127
	v_mov_b32_e32 v43, v127
	v_mov_b32_e32 v42, v127
	v_mov_b32_e32 v41, v127
	v_mov_b32_e32 v40, v127
	v_mov_b32_e32 v31, v127
	v_mov_b32_e32 v30, v127
	v_mov_b32_e32 v29, v127
	v_mov_b32_e32 v28, v127
	v_mov_b32_e32 v27, v127
	v_mov_b32_e32 v26, v127
	v_mov_b32_e32 v25, v127
	v_mov_b32_e32 v24, v127
	v_mov_b32_e32 v15, v127
	v_mov_b32_e32 v14, v127
	v_mov_b32_e32 v13, v127
	v_mov_b32_e32 v12, v127
	v_mov_b32_e32 v11, v127
	v_mov_b32_e32 v10, v127
	v_mov_b32_e32 v9, v127
	v_mov_b32_e32 v8, v127
	v_mov_b32_e32 v55, v127
	v_mov_b32_e32 v54, v127
	v_mov_b32_e32 v53, v127
	v_mov_b32_e32 v52, v127
	v_mov_b32_e32 v51, v127
	v_mov_b32_e32 v50, v127
	v_mov_b32_e32 v49, v127
	v_mov_b32_e32 v48, v127
	v_mov_b32_e32 v39, v127
	v_mov_b32_e32 v38, v127
	v_mov_b32_e32 v37, v127
	v_mov_b32_e32 v36, v127
	v_mov_b32_e32 v35, v127
	v_mov_b32_e32 v34, v127
	v_mov_b32_e32 v33, v127
	v_mov_b32_e32 v32, v127
	v_mov_b32_e32 v23, v127
	v_mov_b32_e32 v22, v127
	v_mov_b32_e32 v21, v127
	v_mov_b32_e32 v20, v127
	v_mov_b32_e32 v19, v127
	v_mov_b32_e32 v18, v127
	v_mov_b32_e32 v17, v127
	v_mov_b32_e32 v16, v127
	v_mov_b32_e32 v7, v127
	v_mov_b32_e32 v6, v127
	v_mov_b32_e32 v5, v127
	v_mov_b32_e32 v4, v127
	v_mov_b32_e32 v3, v127
	v_mov_b32_e32 v2, v127
	v_mov_b32_e32 v1, v127
	v_mov_b32_e32 v0, v127
	s_branch .LBB0_971
.Lzskip_7:
	s_add_u32 s2, s6, 0x80
	s_addc_u32 s3, s7, 0
	s_add_u32 s6, s4, 0x100
	v_mov_b32_e32 v0, 0
	s_addc_u32 s7, s5, 0
	s_mov_b32 s4, 0
	v_mov_b32_e32 v1, v0
	v_mov_b32_e32 v2, v0
	v_mov_b32_e32 v3, v0
	v_mov_b32_e32 v4, v0
	v_mov_b32_e32 v5, v0
	v_mov_b32_e32 v6, v0
	v_mov_b32_e32 v7, v0
	v_mov_b32_e32 v16, v0
	v_mov_b32_e32 v17, v0
	v_mov_b32_e32 v18, v0
	v_mov_b32_e32 v19, v0
	v_mov_b32_e32 v20, v0
	v_mov_b32_e32 v21, v0
	v_mov_b32_e32 v22, v0
	v_mov_b32_e32 v23, v0
	v_mov_b32_e32 v32, v0
	v_mov_b32_e32 v33, v0
	v_mov_b32_e32 v34, v0
	v_mov_b32_e32 v35, v0
	v_mov_b32_e32 v36, v0
	v_mov_b32_e32 v37, v0
	v_mov_b32_e32 v38, v0
	v_mov_b32_e32 v39, v0
	v_mov_b32_e32 v48, v0
	v_mov_b32_e32 v49, v0
	v_mov_b32_e32 v50, v0
	v_mov_b32_e32 v51, v0
	v_mov_b32_e32 v52, v0
	v_mov_b32_e32 v53, v0
	v_mov_b32_e32 v54, v0
	v_mov_b32_e32 v55, v0
	v_mov_b32_e32 v8, v0
	v_mov_b32_e32 v9, v0
	v_mov_b32_e32 v10, v0
	v_mov_b32_e32 v11, v0
	v_mov_b32_e32 v12, v0
	v_mov_b32_e32 v13, v0
	v_mov_b32_e32 v14, v0
	v_mov_b32_e32 v15, v0
	v_mov_b32_e32 v24, v0
	v_mov_b32_e32 v25, v0
	v_mov_b32_e32 v26, v0
	v_mov_b32_e32 v27, v0
	v_mov_b32_e32 v28, v0
	v_mov_b32_e32 v29, v0
	v_mov_b32_e32 v30, v0
	v_mov_b32_e32 v31, v0
	v_mov_b32_e32 v40, v0
	v_mov_b32_e32 v41, v0
	v_mov_b32_e32 v42, v0
	v_mov_b32_e32 v43, v0
	v_mov_b32_e32 v44, v0
	v_mov_b32_e32 v45, v0
	v_mov_b32_e32 v46, v0
	v_mov_b32_e32 v47, v0
	v_mov_b32_e32 v56, v0
	v_mov_b32_e32 v57, v0
	v_mov_b32_e32 v58, v0
	v_mov_b32_e32 v59, v0
	v_mov_b32_e32 v60, v0
	v_mov_b32_e32 v61, v0
	v_mov_b32_e32 v62, v0
	v_mov_b32_e32 v63, v0
	v_mov_b32_e32 v64, v0
	v_mov_b32_e32 v65, v0
	v_mov_b32_e32 v66, v0
	v_mov_b32_e32 v67, v0
	v_mov_b32_e32 v68, v0
	v_mov_b32_e32 v69, v0
	v_mov_b32_e32 v70, v0
	v_mov_b32_e32 v71, v0
	v_mov_b32_e32 v80, v0
	v_mov_b32_e32 v81, v0
	v_mov_b32_e32 v82, v0
	v_mov_b32_e32 v83, v0
	v_mov_b32_e32 v84, v0
	v_mov_b32_e32 v85, v0
	v_mov_b32_e32 v86, v0
	v_mov_b32_e32 v87, v0
	v_mov_b32_e32 v96, v0
	v_mov_b32_e32 v97, v0
	v_mov_b32_e32 v98, v0
	v_mov_b32_e32 v99, v0
	v_mov_b32_e32 v100, v0
	v_mov_b32_e32 v101, v0
	v_mov_b32_e32 v102, v0
	v_mov_b32_e32 v103, v0
	v_mov_b32_e32 v112, v0
	v_mov_b32_e32 v113, v0
	v_mov_b32_e32 v114, v0
	v_mov_b32_e32 v115, v0
	v_mov_b32_e32 v116, v0
	v_mov_b32_e32 v117, v0
	v_mov_b32_e32 v118, v0
	v_mov_b32_e32 v119, v0
	v_mov_b32_e32 v72, v0
	v_mov_b32_e32 v73, v0
	v_mov_b32_e32 v74, v0
	v_mov_b32_e32 v75, v0
	v_mov_b32_e32 v76, v0
	v_mov_b32_e32 v77, v0
	v_mov_b32_e32 v78, v0
	v_mov_b32_e32 v79, v0
	v_mov_b32_e32 v88, v0
	v_mov_b32_e32 v89, v0
	v_mov_b32_e32 v90, v0
	v_mov_b32_e32 v91, v0
	v_mov_b32_e32 v92, v0
	v_mov_b32_e32 v93, v0
	v_mov_b32_e32 v94, v0
	v_mov_b32_e32 v95, v0
	v_mov_b32_e32 v104, v0
	v_mov_b32_e32 v105, v0
	v_mov_b32_e32 v106, v0
	v_mov_b32_e32 v107, v0
	v_mov_b32_e32 v108, v0
	v_mov_b32_e32 v109, v0
	v_mov_b32_e32 v110, v0
	v_mov_b32_e32 v111, v0
	v_mov_b32_e32 v120, v0
	v_mov_b32_e32 v121, v0
	v_mov_b32_e32 v122, v0
	v_mov_b32_e32 v123, v0
	v_mov_b32_e32 v124, v0
	v_mov_b32_e32 v125, v0
	v_mov_b32_e32 v126, v0
	v_mov_b32_e32 v127, v0

.LBB0_1157:
	s_andn2_b64 vcc, exec, s[22:23]
	s_cbranch_vccz .Lzskip_8
	v_mov_b32_e32 v127, 0
	v_mov_b32_e32 v126, v127
	v_mov_b32_e32 v125, v127
	v_mov_b32_e32 v124, v127
	v_mov_b32_e32 v123, v127
	v_mov_b32_e32 v122, v127
	v_mov_b32_e32 v121, v127
	v_mov_b32_e32 v120, v127
	v_mov_b32_e32 v111, v127
	v_mov_b32_e32 v110, v127
	v_mov_b32_e32 v109, v127
	v_mov_b32_e32 v108, v127
	v_mov_b32_e32 v107, v127
	v_mov_b32_e32 v106, v127
	v_mov_b32_e32 v105, v127
	v_mov_b32_e32 v104, v127
	v_mov_b32_e32 v95, v127
	v_mov_b32_e32 v94, v127
	v_mov_b32_e32 v93, v127
	v_mov_b32_e32 v92, v127
	v_mov_b32_e32 v91, v127
	v_mov_b32_e32 v90, v127
	v_mov_b32_e32 v89, v127
	v_mov_b32_e32 v88, v127
	v_mov_b32_e32 v79, v127
	v_mov_b32_e32 v78, v127
	v_mov_b32_e32 v77, v127
	v_mov_b32_e32 v76, v127
	v_mov_b32_e32 v75, v127
	v_mov_b32_e32 v74, v127
	v_mov_b32_e32 v73, v127
	v_mov_b32_e32 v72, v127
	v_mov_b32_e32 v119, v127
	v_mov_b32_e32 v118, v127
	v_mov_b32_e32 v117, v127
	v_mov_b32_e32 v116, v127
	v_mov_b32_e32 v115, v127
	v_mov_b32_e32 v114, v127
	v_mov_b32_e32 v113, v127
	v_mov_b32_e32 v112, v127
	v_mov_b32_e32 v103, v127
	v_mov_b32_e32 v102, v127
	v_mov_b32_e32 v101, v127
	v_mov_b32_e32 v100, v127
	v_mov_b32_e32 v99, v127
	v_mov_b32_e32 v98, v127
	v_mov_b32_e32 v97, v127
	v_mov_b32_e32 v96, v127
	v_mov_b32_e32 v87, v127
	v_mov_b32_e32 v86, v127
	v_mov_b32_e32 v85, v127
	v_mov_b32_e32 v84, v127
	v_mov_b32_e32 v83, v127
	v_mov_b32_e32 v82, v127
	v_mov_b32_e32 v81, v127
	v_mov_b32_e32 v80, v127
	v_mov_b32_e32 v71, v127
	v_mov_b32_e32 v70, v127
	v_mov_b32_e32 v69, v127
	v_mov_b32_e32 v68, v127
	v_mov_b32_e32 v67, v127
	v_mov_b32_e32 v66, v127
	v_mov_b32_e32 v65, v127
	v_mov_b32_e32 v64, v127
	v_mov_b32_e32 v63, v127
	v_mov_b32_e32 v62, v127
	v_mov_b32_e32 v61, v127
	v_mov_b32_e32 v60, v127
	v_mov_b32_e32 v59, v127
	v_mov_b32_e32 v58, v127
	v_mov_b32_e32 v57, v127
	v_mov_b32_e32 v56, v127
	v_mov_b32_e32 v47, v127
	v_mov_b32_e32 v46, v127
	v_mov_b32_e32 v45, v127
	v_mov_b32_e32 v44, v127
	v_mov_b32_e32 v43, v127
	v_mov_b32_e32 v42, v127
	v_mov_b32_e32 v41, v127
	v_mov_b32_e32 v40, v127
	v_mov_b32_e32 v31, v127
	v_mov_b32_e32 v30, v127
	v_mov_b32_e32 v29, v127
	v_mov_b32_e32 v28, v127
	v_mov_b32_e32 v27, v127
	v_mov_b32_e32 v26, v127
	v_mov_b32_e32 v25, v127
	v_mov_b32_e32 v24, v127
	v_mov_b32_e32 v15, v127
	v_mov_b32_e32 v14, v127
	v_mov_b32_e32 v13, v127
	v_mov_b32_e32 v12, v127
	v_mov_b32_e32 v11, v127
	v_mov_b32_e32 v10, v127
	v_mov_b32_e32 v9, v127
	v_mov_b32_e32 v8, v127
	v_mov_b32_e32 v55, v127
	v_mov_b32_e32 v54, v127
	v_mov_b32_e32 v53, v127
	v_mov_b32_e32 v52, v127
	v_mov_b32_e32 v51, v127
	v_mov_b32_e32 v50, v127
	v_mov_b32_e32 v49, v127
	v_mov_b32_e32 v48, v127
	v_mov_b32_e32 v39, v127
	v_mov_b32_e32 v38, v127
	v_mov_b32_e32 v37, v127
	v_mov_b32_e32 v36, v127
	v_mov_b32_e32 v35, v127
	v_mov_b32_e32 v34, v127
	v_mov_b32_e32 v33, v127
	v_mov_b32_e32 v32, v127
	v_mov_b32_e32 v23, v127
	v_mov_b32_e32 v22, v127
	v_mov_b32_e32 v21, v127
	v_mov_b32_e32 v20, v127
	v_mov_b32_e32 v19, v127
	v_mov_b32_e32 v18, v127
	v_mov_b32_e32 v17, v127
	v_mov_b32_e32 v16, v127
	v_mov_b32_e32 v7, v127
	v_mov_b32_e32 v6, v127
	v_mov_b32_e32 v5, v127
	v_mov_b32_e32 v4, v127
	v_mov_b32_e32 v3, v127
	v_mov_b32_e32 v2, v127
	v_mov_b32_e32 v1, v127
	v_mov_b32_e32 v0, v127
	s_branch .LBB0_1160
.Lzskip_8:
	s_add_u32 s0, s38, 0x80
	s_addc_u32 s1, s39, 0
	s_add_u32 s38, s6, 0x100
	v_mov_b32_e32 v0, 0
	s_addc_u32 s39, s7, 0
	s_mov_b32 s6, 0
	v_mov_b32_e32 v1, v0
	v_mov_b32_e32 v2, v0
	v_mov_b32_e32 v3, v0
	v_mov_b32_e32 v4, v0
	v_mov_b32_e32 v5, v0
	v_mov_b32_e32 v6, v0
	v_mov_b32_e32 v7, v0
	v_mov_b32_e32 v16, v0
	v_mov_b32_e32 v17, v0
	v_mov_b32_e32 v18, v0
	v_mov_b32_e32 v19, v0
	v_mov_b32_e32 v20, v0
	v_mov_b32_e32 v21, v0
	v_mov_b32_e32 v22, v0
	v_mov_b32_e32 v23, v0
	v_mov_b32_e32 v32, v0
	v_mov_b32_e32 v33, v0
	v_mov_b32_e32 v34, v0
	v_mov_b32_e32 v35, v0
	v_mov_b32_e32 v36, v0
	v_mov_b32_e32 v37, v0
	v_mov_b32_e32 v38, v0
	v_mov_b32_e32 v39, v0
	v_mov_b32_e32 v48, v0
	v_mov_b32_e32 v49, v0
	v_mov_b32_e32 v50, v0
	v_mov_b32_e32 v51, v0
	v_mov_b32_e32 v52, v0
	v_mov_b32_e32 v53, v0
	v_mov_b32_e32 v54, v0
	v_mov_b32_e32 v55, v0
	v_mov_b32_e32 v8, v0
	v_mov_b32_e32 v9, v0
	v_mov_b32_e32 v10, v0
	v_mov_b32_e32 v11, v0
	v_mov_b32_e32 v12, v0
	v_mov_b32_e32 v13, v0
	v_mov_b32_e32 v14, v0
	v_mov_b32_e32 v15, v0
	v_mov_b32_e32 v24, v0
	v_mov_b32_e32 v25, v0
	v_mov_b32_e32 v26, v0
	v_mov_b32_e32 v27, v0
	v_mov_b32_e32 v28, v0
	v_mov_b32_e32 v29, v0
	v_mov_b32_e32 v30, v0
	v_mov_b32_e32 v31, v0
	v_mov_b32_e32 v40, v0
	v_mov_b32_e32 v41, v0
	v_mov_b32_e32 v42, v0
	v_mov_b32_e32 v43, v0
	v_mov_b32_e32 v44, v0
	v_mov_b32_e32 v45, v0
	v_mov_b32_e32 v46, v0
	v_mov_b32_e32 v47, v0
	v_mov_b32_e32 v56, v0
	v_mov_b32_e32 v57, v0
	v_mov_b32_e32 v58, v0
	v_mov_b32_e32 v59, v0
	v_mov_b32_e32 v60, v0
	v_mov_b32_e32 v61, v0
	v_mov_b32_e32 v62, v0
	v_mov_b32_e32 v63, v0
	v_mov_b32_e32 v64, v0
	v_mov_b32_e32 v65, v0
	v_mov_b32_e32 v66, v0
	v_mov_b32_e32 v67, v0
	v_mov_b32_e32 v68, v0
	v_mov_b32_e32 v69, v0
	v_mov_b32_e32 v70, v0
	v_mov_b32_e32 v71, v0
	v_mov_b32_e32 v80, v0
	v_mov_b32_e32 v81, v0
	v_mov_b32_e32 v82, v0
	v_mov_b32_e32 v83, v0
	v_mov_b32_e32 v84, v0
	v_mov_b32_e32 v85, v0
	v_mov_b32_e32 v86, v0
	v_mov_b32_e32 v87, v0
	v_mov_b32_e32 v96, v0
	v_mov_b32_e32 v97, v0
	v_mov_b32_e32 v98, v0
	v_mov_b32_e32 v99, v0
	v_mov_b32_e32 v100, v0
	v_mov_b32_e32 v101, v0
	v_mov_b32_e32 v102, v0
	v_mov_b32_e32 v103, v0
	v_mov_b32_e32 v112, v0
	v_mov_b32_e32 v113, v0
	v_mov_b32_e32 v114, v0
	v_mov_b32_e32 v115, v0
	v_mov_b32_e32 v116, v0
	v_mov_b32_e32 v117, v0
	v_mov_b32_e32 v118, v0
	v_mov_b32_e32 v119, v0
	v_mov_b32_e32 v72, v0
	v_mov_b32_e32 v73, v0
	v_mov_b32_e32 v74, v0
	v_mov_b32_e32 v75, v0
	v_mov_b32_e32 v76, v0
	v_mov_b32_e32 v77, v0
	v_mov_b32_e32 v78, v0
	v_mov_b32_e32 v79, v0
	v_mov_b32_e32 v88, v0
	v_mov_b32_e32 v89, v0
	v_mov_b32_e32 v90, v0
	v_mov_b32_e32 v91, v0
	v_mov_b32_e32 v92, v0
	v_mov_b32_e32 v93, v0
	v_mov_b32_e32 v94, v0
	v_mov_b32_e32 v95, v0
	v_mov_b32_e32 v104, v0
	v_mov_b32_e32 v105, v0
	v_mov_b32_e32 v106, v0
	v_mov_b32_e32 v107, v0
	v_mov_b32_e32 v108, v0
	v_mov_b32_e32 v109, v0
	v_mov_b32_e32 v110, v0
	v_mov_b32_e32 v111, v0
	v_mov_b32_e32 v120, v0
	v_mov_b32_e32 v121, v0
	v_mov_b32_e32 v122, v0
	v_mov_b32_e32 v123, v0
	v_mov_b32_e32 v124, v0
	v_mov_b32_e32 v125, v0
	v_mov_b32_e32 v126, v0
	v_mov_b32_e32 v127, v0
